# pooling-branch item rewritten by hand: coalesced row loads issued up front, wave-balanced window sums, gates and outputs through an LDS tile
# speedup vs baseline: 1.0566x; 1.0187x over previous
; DI void pool_item(const Params& p, int l, int token0, char* lds) {
;     ...
;   if (token0 < NLAT) { seqbase = (token0 / SEQ) * SEQ; L = SEQ; }
;   else { seqbase = NLAT + ((token0 - NLAT) / CTX) * CTX; L = CTX; }
;   const int s0 = token0 - seqbase;
;   char* zt = lds;
;   char* pl = lds + 40960;
;   f32x4 scp[2][4];
;   u32x2 gvp[2][4];
;   {
;     const int g_ = w & 3, tok_ = token0 + (w >> 2) * 32 + r;
; #pragma unroll
;     for (int mo = 0; mo < 2; ++mo)
; #pragma unroll
;       for (int gg = 0; gg < 4; ++gg) {
;         const int oc = mo * 32 + 8 * gg + 4 * h;
;         scp[mo][gg] = *(const f32x4*)(p.pool_scale + l * 256 + g_ * 64 + oc);
;         gvp[mo][gg] = *(const u32x2*)(p.P + (size_t)tok_ * INW + 1536 + g_ * 64 + oc);
;       }
;   }
;   for (int e = tid; e < 80 * 32; e += NTHREADS) {
;     const int row = e >> 5, ch = e & 31;
;     const int s = s0 - 8 + row;
;     u32x4 v = {0u, 0u, 0u, 0u};
;     if (s >= 0 && s < L) v = *(const u32x4*)(p.P + (size_t)(seqbase + s) * INW + 1280 + ch * 8);
;     *(u32x4*)(zt + row * 512 + ch * 16) = v;
;   }
;   __syncthreads();
;     ...
;     const bf16_t* wp = p.pwT + (size_t)((l * 4 + g) * 64) * 64;
; #pragma unroll
;     for (int ks = 0; ks < 4; ++ks) {
;       bf16x8 a[2], b[2];
; #pragma unroll
;       for (int mo = 0; mo < 2; ++mo) a[mo] = *(const bf16x8*)(wp + (size_t)(mo * 32 + r) * 64 + ks * 16 + h * 8);
.LBB0_83:
	v_readlane_b32 s0, v255, 17
	s_cmp_lt_i32 s83, s0
	s_mov_b64 s[2:3], -1
	s_cbranch_scc1 .LBB0_97
	v_readlane_b32 s0, v255, 17
	v_readlane_b32 s14, v254, 49
	v_readlane_b32 s15, v254, 50
	v_readlane_b32 s16, v254, 55
	v_readlane_b32 s17, v254, 56
	v_readlane_b32 s18, v254, 45
	v_readlane_b32 s19, v254, 46
	v_readlane_b32 s20, v255, 15
	v_readlane_b32 s21, v255, 16
	v_readlane_b32 s22, v255, 12
	s_nop 3
	s_sub_i32 s0, s83, s0
	s_lshl_b32 s4, s0, 6
	s_cmp_lt_u32 s4, 0x8000
	s_movk_i32 s2, 0x100
	s_cselect_b32 s5, 0x800, s2
	s_movk_i32 s2, 0xff
	s_cselect_b32 s2, 0x7ff, s2
	s_and_b32 s6, s4, s2
	s_sub_i32 s2, s4, 8
	s_ashr_i32 s3, s2, 31
	s_mul_i32 s7, s2, 0x1600
	s_mul_hi_i32 s23, s2, 0x1600
	s_add_u32 s24, s14, s7
	s_addc_u32 s25, s15, s23
	s_add_u32 s24, s24, 0xa00
	s_addc_u32 s25, s25, 0
	s_mul_i32 s7, s4, 0x1600
	s_mul_hi_u32 s23, s4, 0x1600
	s_add_u32 s26, s14, s7
	s_addc_u32 s27, s15, s23
	s_add_u32 s26, s26, 0xc00
	s_addc_u32 s27, s27, 0
	s_lshl_b32 s7, s4, 11
	s_add_u32 s16, s16, s7
	s_addc_u32 s17, s17, 0
	s_add_u32 s16, s16, 0x400
	s_addc_u32 s17, s17, 0
	v_lshrrev_b32_e32 v134, 5, v251
	v_and_b32_e32 v135, 31, v251
	v_mul_u32_u24_e32 v136, 0x1600, v134
	v_lshl_add_u32 v136, v135, 4, v136
	s_sub_i32 s2, s6, 8
	v_mov_b32_e32 v0, v134
	v_add_u32_e32 v0, s2, v0
	v_cmp_gt_u32_e32 vcc, s5, v0
	v_mov_b32_e32 v2, 0
	v_mov_b32_e32 v3, 0
	v_mov_b32_e32 v4, 0
	v_mov_b32_e32 v5, 0
	s_and_saveexec_b64 s[8:9], vcc
	global_load_dwordx4 v[2:5], v136, s[24:25]
	s_mov_b64 exec, s[8:9]
	v_add_u32_e32 v0, 16, v134
	v_add_u32_e32 v0, s2, v0
	v_cmp_gt_u32_e32 vcc, s5, v0
	v_mov_b32_e32 v6, 0
	v_mov_b32_e32 v7, 0
	v_mov_b32_e32 v8, 0
	v_mov_b32_e32 v9, 0
	s_and_saveexec_b64 s[8:9], vcc
	v_add_u32_e32 v137, 0x16000, v136
	global_load_dwordx4 v[6:9], v137, s[24:25]
	s_mov_b64 exec, s[8:9]
	v_add_u32_e32 v0, 32, v134
	v_add_u32_e32 v0, s2, v0
	v_cmp_gt_u32_e32 vcc, s5, v0
	v_mov_b32_e32 v10, 0
	v_mov_b32_e32 v11, 0
	v_mov_b32_e32 v12, 0
	v_mov_b32_e32 v13, 0
	s_and_saveexec_b64 s[8:9], vcc
	v_add_u32_e32 v137, 0x2c000, v136
	global_load_dwordx4 v[10:13], v137, s[24:25]
	s_mov_b64 exec, s[8:9]
	v_add_u32_e32 v0, 48, v134
	v_add_u32_e32 v0, s2, v0
	v_cmp_gt_u32_e32 vcc, s5, v0
	v_mov_b32_e32 v14, 0
	v_mov_b32_e32 v15, 0
	v_mov_b32_e32 v16, 0
	v_mov_b32_e32 v17, 0
	s_and_saveexec_b64 s[8:9], vcc
	v_add_u32_e32 v137, 0x42000, v136
	global_load_dwordx4 v[14:17], v137, s[24:25]
	s_mov_b64 exec, s[8:9]
	v_add_u32_e32 v0, 64, v134
	v_add_u32_e32 v0, s2, v0
	v_cmp_gt_u32_e32 vcc, s5, v0
	v_mov_b32_e32 v18, 0
	v_mov_b32_e32 v19, 0
	v_mov_b32_e32 v20, 0
	v_mov_b32_e32 v21, 0
	s_and_saveexec_b64 s[8:9], vcc
	v_add_u32_e32 v137, 0x58000, v136
	global_load_dwordx4 v[18:21], v137, s[24:25]
	s_mov_b64 exec, s[8:9]
	v_mov_b32_e32 v0, v134
	v_xor_b32_e32 v138, v135, v0
	v_and_b32_e32 v139, 31, v0
	v_xor_b32_e32 v138, v135, v139
	v_mul_u32_u24_e32 v139, 0x1600, v0
	v_lshl_add_u32 v139, v138, 4, v139
	global_load_dwordx4 v[22:25], v139, s[26:27]
	v_add_u32_e32 v0, 16, v134
	v_xor_b32_e32 v138, v135, v0
	v_and_b32_e32 v139, 31, v0
	v_xor_b32_e32 v138, v135, v139
	v_mul_u32_u24_e32 v139, 0x1600, v0
	v_lshl_add_u32 v139, v138, 4, v139
	global_load_dwordx4 v[26:29], v139, s[26:27]
	v_add_u32_e32 v0, 32, v134
	v_xor_b32_e32 v138, v135, v0
	v_and_b32_e32 v139, 31, v0
	v_xor_b32_e32 v138, v135, v139
	v_mul_u32_u24_e32 v139, 0x1600, v0
	v_lshl_add_u32 v139, v138, 4, v139
	global_load_dwordx4 v[30:33], v139, s[26:27]
	v_add_u32_e32 v0, 48, v134
	v_xor_b32_e32 v138, v135, v0
	v_and_b32_e32 v139, 31, v0
	v_xor_b32_e32 v138, v135, v139
	v_mul_u32_u24_e32 v139, 0x1600, v0
	v_lshl_add_u32 v139, v138, 4, v139
	global_load_dwordx4 v[34:37], v139, s[26:27]
	v_lshrrev_b32_e32 v140, 6, v251
	s_nop 0
	v_readfirstlane_b32 s28, v140
	s_nop 3
	s_and_b32 s29, s28, 3
	s_add_i32 s2, s22, s29
	s_lshl_b32 s2, s2, 13
	s_add_u32 s18, s18, s2
	s_addc_u32 s19, s19, 0
	s_lshl_b32 s2, s29, 8
	s_add_u32 s20, s20, s2
	s_addc_u32 s21, s21, 0
	v_and_b32_e32 v141, 31, v251
	v_bfe_u32 v142, v251, 5, 1
	v_lshlrev_b32_e32 v143, 7, v141
	v_lshl_or_b32 v143, v142, 4, v143
	v_add_u32_e32 v159, 0x1000, v143
	global_load_dwordx4 v[38:41], v143, s[18:19]
	global_load_dwordx4 v[42:45], v159, s[18:19]
	global_load_dwordx4 v[46:49], v143, s[18:19] offset:32
	global_load_dwordx4 v[50:53], v159, s[18:19] offset:32
	global_load_dwordx4 v[54:57], v143, s[18:19] offset:64
	global_load_dwordx4 v[58:61], v159, s[18:19] offset:64
	global_load_dwordx4 v[62:65], v143, s[18:19] offset:96
	global_load_dwordx4 v[66:69], v159, s[18:19] offset:96
	v_lshlrev_b32_e32 v144, 4, v142
	global_load_dwordx4 v[70:73], v144, s[20:21] offset:0
	global_load_dwordx4 v[74:77], v144, s[20:21] offset:32
	global_load_dwordx4 v[78:81], v144, s[20:21] offset:64
	global_load_dwordx4 v[82:85], v144, s[20:21] offset:96
	global_load_dwordx4 v[86:89], v144, s[20:21] offset:128
	global_load_dwordx4 v[90:93], v144, s[20:21] offset:160
	global_load_dwordx4 v[94:97], v144, s[20:21] offset:192
	global_load_dwordx4 v[98:101], v144, s[20:21] offset:224
	v_lshlrev_b32_e32 v145, 9, v134
	v_and_b32_e32 v146, 1, v134
	v_lshlrev_b32_e32 v146, 3, v146
	v_xor_b32_e32 v146, v146, v135
	v_lshl_or_b32 v145, v146, 4, v145
	s_waitcnt vmcnt(20)
	ds_write_b128 v145, v[2:5]
	ds_write_b128 v145, v[6:9] offset:8192
	ds_write_b128 v145, v[10:13] offset:16384
	ds_write_b128 v145, v[14:17] offset:24576
	ds_write_b128 v145, v[18:21] offset:32768
	v_lshlrev_b32_e32 v147, 9, v134
	v_lshl_or_b32 v147, v135, 4, v147
	v_add_u32_e32 v147, 0x12000, v147
	s_waitcnt vmcnt(16)
	ds_write_b128 v147, v[22:25]
	ds_write_b128 v147, v[26:29] offset:8192
	ds_write_b128 v147, v[30:33] offset:16384
	ds_write_b128 v147, v[34:37] offset:24576
	s_waitcnt lgkmcnt(0)
	s_barrier
	v_and_b32_e32 v148, 63, v251
	s_cmp_lt_u32 s28, 4
	s_cbranch_scc1 .Lpl_g3
	s_cmp_lt_u32 s28, 6
	s_cbranch_scc1 .Lpl_g2
	s_cmp_eq_u32 s28, 6
	s_cbranch_scc1 .Lpl_g1
; DI float bflo(unsigned u) { return __uint_as_float(u << 16); }
; DI float bfhi(unsigned u) { return __uint_as_float(u & 0xffff0000u); }
; DI void pool_item(const Params& p, int l, int token0, char* lds) {
;     ...
;   for (int e = tid; e < 64 * 32; e += NTHREADS) {
;     const int tl = e >> 5, ch = e & 31;
;     const int g = ch >> 3;
;     const int hw = 1 << g;
;     const int s = s0 + tl;
;     int lo = s - hw; lo = lo < 0 ? 0 : lo;
;     int hi = s + hw - 1; hi = hi > L - 1 ? L - 1 : hi;
;     float sum[8];
; #pragma unroll
;     for (int j = 0; j < 8; ++j) sum[j] = 0.f;
;     for (int q = lo; q <= hi; ++q) {
;       const u32x4 v = *(const u32x4*)(zt + (q - s0 + 8) * 512 + ch * 16);
; #pragma unroll
;       for (int j = 0; j < 4; ++j) { sum[2 * j] += bflo(v[j]); sum[2 * j + 1] += bfhi(v[j]); }
;     }
;     const float ic = 1.f / (float)(hi - lo + 1);
;     const u32x4 zc = *(const u32x4*)(zt + (tl + 8) * 512 + ch * 16);
;     u32x4 ov;
; #pragma unroll
;     for (int j = 0; j < 4; ++j)
;       ov[j] = pk2(sum[2 * j] * ic - bflo(zc[j]), sum[2 * j + 1] * ic - bfhi(zc[j]));
;     *(u32x4*)(pl + tl * 512 + ((ch ^ (tl & 15)) << 4)) = ov;
;   }
.Lpl_g0:
	s_sub_u32 s2, s28, 7
	v_mov_b32_e32 v149, s2
	v_lshl_or_b32 v149, v149, 6, v148
	s_mov_b32 s30, 0
.Lpl_g0_k:
	v_add_u32_e32 v150, s30, v149
	v_lshrrev_b32_e32 v151, 3, v150
	v_and_b32_e32 v152, 7, v150
	v_or_b32_e32 v152, 0, v152
	v_add_u32_e32 v153, 7, v151
	v_lshlrev_b32_e32 v154, 9, v153
	v_and_b32_e32 v155, 1, v153
	v_lshlrev_b32_e32 v155, 3, v155
	v_xor_b32_e32 v156, v155, v152
	v_lshl_or_b32 v156, v156, 4, v154
	v_xor_b32_e32 v155, 8, v155
	v_xor_b32_e32 v157, v155, v152
	v_lshl_or_b32 v157, v157, 4, v154
	ds_read_b128 v[102:105], v156 offset:0
	ds_read_b128 v[106:109], v157 offset:512
	v_add_u32_e32 v153, 8, v151
	v_lshlrev_b32_e32 v154, 9, v153
	v_and_b32_e32 v155, 1, v153
	v_lshlrev_b32_e32 v155, 3, v155
	v_xor_b32_e32 v155, v155, v152
	v_lshl_or_b32 v154, v155, 4, v154
	ds_read_b128 v[224:227], v154
	v_add_u32_e32 v153, s6, v151
	v_subrev_u32_e32 v154, 1, v153
	v_max_i32_e32 v154, 0, v154
	v_add_u32_e32 v155, 0, v153
	s_sub_i32 s3, s5, 1
	v_min_i32_e32 v155, s3, v155
	v_sub_u32_e32 v155, v155, v154
	v_add_u32_e32 v155, 1, v155
	v_cvt_f32_i32_e32 v155, v155
	v_div_scale_f32 v228, s[2:3], v155, v155, 1.0
	v_rcp_f32_e32 v229, v228
	s_nop 0
	v_fma_f32 v230, -v228, v229, 1.0
	v_fmac_f32_e32 v229, v230, v229
	v_div_scale_f32 v230, vcc, 1.0, v155, 1.0
	v_mul_f32_e32 v232, v230, v229
	v_fma_f32 v233, -v228, v232, v230
	v_fmac_f32_e32 v232, v233, v229
	v_fma_f32 v228, -v228, v232, v230
	v_div_fmas_f32 v228, v228, v229, v232
	v_div_fixup_f32 v158, v228, v155, 1.0
	s_waitcnt lgkmcnt(2)
	v_lshlrev_b32_e32 v232, 16, v102
	v_and_b32_e32 v233, 0xffff0000, v102
	v_lshlrev_b32_e32 v234, 16, v103
	v_and_b32_e32 v235, 0xffff0000, v103
	v_lshlrev_b32_e32 v236, 16, v104
	v_and_b32_e32 v237, 0xffff0000, v104
	v_lshlrev_b32_e32 v238, 16, v105
	v_and_b32_e32 v239, 0xffff0000, v105
	s_waitcnt lgkmcnt(1)
	v_lshlrev_b32_e32 v228, 16, v106
	v_and_b32_e32 v229, 0xffff0000, v106
	v_pk_add_f32 v[232:233], v[232:233], v[228:229]
	v_lshlrev_b32_e32 v228, 16, v107
	v_and_b32_e32 v229, 0xffff0000, v107
	v_pk_add_f32 v[234:235], v[234:235], v[228:229]
	v_lshlrev_b32_e32 v228, 16, v108
	v_and_b32_e32 v229, 0xffff0000, v108
	v_pk_add_f32 v[236:237], v[236:237], v[228:229]
	v_lshlrev_b32_e32 v228, 16, v109
	v_and_b32_e32 v229, 0xffff0000, v109
	v_pk_add_f32 v[238:239], v[238:239], v[228:229]
	s_waitcnt lgkmcnt(0)
	v_lshlrev_b32_e32 v228, 16, v224
	v_and_b32_e32 v229, 0xffff0000, v224
	v_pk_fma_f32 v[232:233], v[158:159], v[232:233], v[228:229] op_sel_hi:[0,1,1] neg_lo:[0,0,1] neg_hi:[0,0,1]
	v_lshlrev_b32_e32 v228, 16, v225
	v_and_b32_e32 v229, 0xffff0000, v225
	v_pk_fma_f32 v[234:235], v[158:159], v[234:235], v[228:229] op_sel_hi:[0,1,1] neg_lo:[0,0,1] neg_hi:[0,0,1]
	v_lshlrev_b32_e32 v228, 16, v226
	v_and_b32_e32 v229, 0xffff0000, v226
	v_pk_fma_f32 v[236:237], v[158:159], v[236:237], v[228:229] op_sel_hi:[0,1,1] neg_lo:[0,0,1] neg_hi:[0,0,1]
	v_lshlrev_b32_e32 v228, 16, v227
	v_and_b32_e32 v229, 0xffff0000, v227
	v_pk_fma_f32 v[238:239], v[158:159], v[238:239], v[228:229] op_sel_hi:[0,1,1] neg_lo:[0,0,1] neg_hi:[0,0,1]
	v_cvt_pk_bf16_f32 v224, v232, v233
	v_cvt_pk_bf16_f32 v225, v234, v235
	v_cvt_pk_bf16_f32 v226, v236, v237
	v_cvt_pk_bf16_f32 v227, v238, v239
	v_and_b32_e32 v153, 15, v151
	v_xor_b32_e32 v153, v153, v152
	v_lshlrev_b32_e32 v154, 9, v151
	v_lshl_or_b32 v154, v153, 4, v154
	ds_write_b128 v154, v[224:227] offset:40960
	s_addk_i32 s30, 64
	s_cmpk_lt_u32 s30, 0x200
	s_cbranch_scc1 .Lpl_g0_k
	s_branch .Lpl_done
.Lpl_g1:
	s_sub_u32 s2, s28, 6
	v_mov_b32_e32 v149, s2
	v_lshl_or_b32 v149, v149, 6, v148
	s_mov_b32 s30, 0
.Lpl_g1_k:
	v_add_u32_e32 v150, s30, v149
	v_lshrrev_b32_e32 v151, 3, v150
	v_and_b32_e32 v152, 7, v150
	v_or_b32_e32 v152, 8, v152
	v_add_u32_e32 v153, 6, v151
	v_lshlrev_b32_e32 v154, 9, v153
	v_and_b32_e32 v155, 1, v153
	v_lshlrev_b32_e32 v155, 3, v155
	v_xor_b32_e32 v156, v155, v152
	v_lshl_or_b32 v156, v156, 4, v154
	v_xor_b32_e32 v155, 8, v155
	v_xor_b32_e32 v157, v155, v152
	v_lshl_or_b32 v157, v157, 4, v154
	ds_read_b128 v[102:105], v156 offset:0
	ds_read_b128 v[106:109], v157 offset:512
	ds_read_b128 v[110:113], v156 offset:1024
	ds_read_b128 v[114:117], v157 offset:1536
	v_add_u32_e32 v153, 8, v151
	v_lshlrev_b32_e32 v154, 9, v153
	v_and_b32_e32 v155, 1, v153
	v_lshlrev_b32_e32 v155, 3, v155
	v_xor_b32_e32 v155, v155, v152
	v_lshl_or_b32 v154, v155, 4, v154
	ds_read_b128 v[224:227], v154
	v_add_u32_e32 v153, s6, v151
	v_subrev_u32_e32 v154, 2, v153
	v_max_i32_e32 v154, 0, v154
	v_add_u32_e32 v155, 1, v153
	s_sub_i32 s3, s5, 1
	v_min_i32_e32 v155, s3, v155
	v_sub_u32_e32 v155, v155, v154
	v_add_u32_e32 v155, 1, v155
	v_cvt_f32_i32_e32 v155, v155
	v_div_scale_f32 v228, s[2:3], v155, v155, 1.0
	v_rcp_f32_e32 v229, v228
	s_nop 0
	v_fma_f32 v230, -v228, v229, 1.0
	v_fmac_f32_e32 v229, v230, v229
	v_div_scale_f32 v230, vcc, 1.0, v155, 1.0
	v_mul_f32_e32 v232, v230, v229
	v_fma_f32 v233, -v228, v232, v230
	v_fmac_f32_e32 v232, v233, v229
	v_fma_f32 v228, -v228, v232, v230
	v_div_fmas_f32 v228, v228, v229, v232
	v_div_fixup_f32 v158, v228, v155, 1.0
	s_waitcnt lgkmcnt(4)
	v_lshlrev_b32_e32 v232, 16, v102
	v_and_b32_e32 v233, 0xffff0000, v102
	v_lshlrev_b32_e32 v234, 16, v103
	v_and_b32_e32 v235, 0xffff0000, v103
	v_lshlrev_b32_e32 v236, 16, v104
	v_and_b32_e32 v237, 0xffff0000, v104
	v_lshlrev_b32_e32 v238, 16, v105
	v_and_b32_e32 v239, 0xffff0000, v105
	s_waitcnt lgkmcnt(3)
; DI float bflo(unsigned u) { return __uint_as_float(u << 16); }
; DI float bfhi(unsigned u) { return __uint_as_float(u & 0xffff0000u); }
; DI void pool_item(const Params& p, int l, int token0, char* lds) {
;     ...
;   for (int e = tid; e < 64 * 32; e += NTHREADS) {
;     const int tl = e >> 5, ch = e & 31;
;     const int g = ch >> 3;
;     const int hw = 1 << g;
;     const int s = s0 + tl;
;     int lo = s - hw; lo = lo < 0 ? 0 : lo;
;     int hi = s + hw - 1; hi = hi > L - 1 ? L - 1 : hi;
;     float sum[8];
; #pragma unroll
;     for (int j = 0; j < 8; ++j) sum[j] = 0.f;
;     for (int q = lo; q <= hi; ++q) {
;       const u32x4 v = *(const u32x4*)(zt + (q - s0 + 8) * 512 + ch * 16);
; #pragma unroll
;       for (int j = 0; j < 4; ++j) { sum[2 * j] += bflo(v[j]); sum[2 * j + 1] += bfhi(v[j]); }
;     }
;     const float ic = 1.f / (float)(hi - lo + 1);
;     const u32x4 zc = *(const u32x4*)(zt + (tl + 8) * 512 + ch * 16);
;     u32x4 ov;
; #pragma unroll
;     for (int j = 0; j < 4; ++j)
;       ov[j] = pk2(sum[2 * j] * ic - bflo(zc[j]), sum[2 * j + 1] * ic - bfhi(zc[j]));
;     *(u32x4*)(pl + tl * 512 + ((ch ^ (tl & 15)) << 4)) = ov;
;   }
	v_lshlrev_b32_e32 v228, 16, v106
	v_and_b32_e32 v229, 0xffff0000, v106
	v_pk_add_f32 v[232:233], v[232:233], v[228:229]
	v_lshlrev_b32_e32 v228, 16, v107
	v_and_b32_e32 v229, 0xffff0000, v107
	v_pk_add_f32 v[234:235], v[234:235], v[228:229]
	v_lshlrev_b32_e32 v228, 16, v108
	v_and_b32_e32 v229, 0xffff0000, v108
	v_pk_add_f32 v[236:237], v[236:237], v[228:229]
	v_lshlrev_b32_e32 v228, 16, v109
	v_and_b32_e32 v229, 0xffff0000, v109
	v_pk_add_f32 v[238:239], v[238:239], v[228:229]
	s_waitcnt lgkmcnt(2)
	v_lshlrev_b32_e32 v228, 16, v110
	v_and_b32_e32 v229, 0xffff0000, v110
	v_pk_add_f32 v[232:233], v[232:233], v[228:229]
	v_lshlrev_b32_e32 v228, 16, v111
	v_and_b32_e32 v229, 0xffff0000, v111
	v_pk_add_f32 v[234:235], v[234:235], v[228:229]
	v_lshlrev_b32_e32 v228, 16, v112
	v_and_b32_e32 v229, 0xffff0000, v112
	v_pk_add_f32 v[236:237], v[236:237], v[228:229]
	v_lshlrev_b32_e32 v228, 16, v113
	v_and_b32_e32 v229, 0xffff0000, v113
	v_pk_add_f32 v[238:239], v[238:239], v[228:229]
	s_waitcnt lgkmcnt(1)
	v_lshlrev_b32_e32 v228, 16, v114
	v_and_b32_e32 v229, 0xffff0000, v114
	v_pk_add_f32 v[232:233], v[232:233], v[228:229]
	v_lshlrev_b32_e32 v228, 16, v115
	v_and_b32_e32 v229, 0xffff0000, v115
	v_pk_add_f32 v[234:235], v[234:235], v[228:229]
	v_lshlrev_b32_e32 v228, 16, v116
	v_and_b32_e32 v229, 0xffff0000, v116
	v_pk_add_f32 v[236:237], v[236:237], v[228:229]
	v_lshlrev_b32_e32 v228, 16, v117
	v_and_b32_e32 v229, 0xffff0000, v117
	v_pk_add_f32 v[238:239], v[238:239], v[228:229]
	s_waitcnt lgkmcnt(0)
	v_lshlrev_b32_e32 v228, 16, v224
	v_and_b32_e32 v229, 0xffff0000, v224
	v_pk_fma_f32 v[232:233], v[158:159], v[232:233], v[228:229] op_sel_hi:[0,1,1] neg_lo:[0,0,1] neg_hi:[0,0,1]
	v_lshlrev_b32_e32 v228, 16, v225
	v_and_b32_e32 v229, 0xffff0000, v225
	v_pk_fma_f32 v[234:235], v[158:159], v[234:235], v[228:229] op_sel_hi:[0,1,1] neg_lo:[0,0,1] neg_hi:[0,0,1]
	v_lshlrev_b32_e32 v228, 16, v226
	v_and_b32_e32 v229, 0xffff0000, v226
	v_pk_fma_f32 v[236:237], v[158:159], v[236:237], v[228:229] op_sel_hi:[0,1,1] neg_lo:[0,0,1] neg_hi:[0,0,1]
	v_lshlrev_b32_e32 v228, 16, v227
	v_and_b32_e32 v229, 0xffff0000, v227
	v_pk_fma_f32 v[238:239], v[158:159], v[238:239], v[228:229] op_sel_hi:[0,1,1] neg_lo:[0,0,1] neg_hi:[0,0,1]
	v_cvt_pk_bf16_f32 v224, v232, v233
	v_cvt_pk_bf16_f32 v225, v234, v235
	v_cvt_pk_bf16_f32 v226, v236, v237
	v_cvt_pk_bf16_f32 v227, v238, v239
	v_and_b32_e32 v153, 15, v151
	v_xor_b32_e32 v153, v153, v152
	v_lshlrev_b32_e32 v154, 9, v151
	v_lshl_or_b32 v154, v153, 4, v154
	ds_write_b128 v154, v[224:227] offset:40960
	s_addk_i32 s30, 64
	s_cmpk_lt_u32 s30, 0x200
	s_cbranch_scc1 .Lpl_g1_k
	s_branch .Lpl_done
.Lpl_g2:
	s_sub_u32 s2, s28, 4
	v_mov_b32_e32 v149, s2
	v_lshl_or_b32 v149, v149, 6, v148
	s_mov_b32 s30, 0
.Lpl_g2_k:
	v_add_u32_e32 v150, s30, v149
	v_lshrrev_b32_e32 v151, 3, v150
	v_and_b32_e32 v152, 7, v150
	v_or_b32_e32 v152, 16, v152
	v_add_u32_e32 v153, 4, v151
	v_lshlrev_b32_e32 v154, 9, v153
	v_and_b32_e32 v155, 1, v153
	v_lshlrev_b32_e32 v155, 3, v155
	v_xor_b32_e32 v156, v155, v152
	v_lshl_or_b32 v156, v156, 4, v154
	v_xor_b32_e32 v155, 8, v155
	v_xor_b32_e32 v157, v155, v152
	v_lshl_or_b32 v157, v157, 4, v154
	ds_read_b128 v[102:105], v156 offset:0
	ds_read_b128 v[106:109], v157 offset:512
	ds_read_b128 v[110:113], v156 offset:1024
	ds_read_b128 v[114:117], v157 offset:1536
	ds_read_b128 v[118:121], v156 offset:2048
	ds_read_b128 v[122:125], v157 offset:2560
	ds_read_b128 v[126:129], v156 offset:3072
	ds_read_b128 v[130:133], v157 offset:3584
	v_add_u32_e32 v153, 8, v151
	v_lshlrev_b32_e32 v154, 9, v153
	v_and_b32_e32 v155, 1, v153
	v_lshlrev_b32_e32 v155, 3, v155
	v_xor_b32_e32 v155, v155, v152
	v_lshl_or_b32 v154, v155, 4, v154
	ds_read_b128 v[224:227], v154
	v_add_u32_e32 v153, s6, v151
	v_subrev_u32_e32 v154, 4, v153
	v_max_i32_e32 v154, 0, v154
	v_add_u32_e32 v155, 3, v153
	s_sub_i32 s3, s5, 1
	v_min_i32_e32 v155, s3, v155
	v_sub_u32_e32 v155, v155, v154
	v_add_u32_e32 v155, 1, v155
	v_cvt_f32_i32_e32 v155, v155
	v_div_scale_f32 v228, s[2:3], v155, v155, 1.0
	v_rcp_f32_e32 v229, v228
	s_nop 0
	v_fma_f32 v230, -v228, v229, 1.0
	v_fmac_f32_e32 v229, v230, v229
	v_div_scale_f32 v230, vcc, 1.0, v155, 1.0
	v_mul_f32_e32 v232, v230, v229
	v_fma_f32 v233, -v228, v232, v230
	v_fmac_f32_e32 v232, v233, v229
	v_fma_f32 v228, -v228, v232, v230
	v_div_fmas_f32 v228, v228, v229, v232
	v_div_fixup_f32 v158, v228, v155, 1.0
	s_waitcnt lgkmcnt(8)
	v_lshlrev_b32_e32 v232, 16, v102
	v_and_b32_e32 v233, 0xffff0000, v102
	v_lshlrev_b32_e32 v234, 16, v103
	v_and_b32_e32 v235, 0xffff0000, v103
	v_lshlrev_b32_e32 v236, 16, v104
	v_and_b32_e32 v237, 0xffff0000, v104
	v_lshlrev_b32_e32 v238, 16, v105
	v_and_b32_e32 v239, 0xffff0000, v105
	s_waitcnt lgkmcnt(7)
	v_lshlrev_b32_e32 v228, 16, v106
	v_and_b32_e32 v229, 0xffff0000, v106
	v_pk_add_f32 v[232:233], v[232:233], v[228:229]
	v_lshlrev_b32_e32 v228, 16, v107
	v_and_b32_e32 v229, 0xffff0000, v107
	v_pk_add_f32 v[234:235], v[234:235], v[228:229]
	v_lshlrev_b32_e32 v228, 16, v108
	v_and_b32_e32 v229, 0xffff0000, v108
	v_pk_add_f32 v[236:237], v[236:237], v[228:229]
	v_lshlrev_b32_e32 v228, 16, v109
	v_and_b32_e32 v229, 0xffff0000, v109
	v_pk_add_f32 v[238:239], v[238:239], v[228:229]
	s_waitcnt lgkmcnt(6)
	v_lshlrev_b32_e32 v228, 16, v110
	v_and_b32_e32 v229, 0xffff0000, v110
	v_pk_add_f32 v[232:233], v[232:233], v[228:229]
	v_lshlrev_b32_e32 v228, 16, v111
	v_and_b32_e32 v229, 0xffff0000, v111
	v_pk_add_f32 v[234:235], v[234:235], v[228:229]
	v_lshlrev_b32_e32 v228, 16, v112
	v_and_b32_e32 v229, 0xffff0000, v112
	v_pk_add_f32 v[236:237], v[236:237], v[228:229]
	v_lshlrev_b32_e32 v228, 16, v113
	v_and_b32_e32 v229, 0xffff0000, v113
	v_pk_add_f32 v[238:239], v[238:239], v[228:229]
	s_waitcnt lgkmcnt(5)
; DI float bflo(unsigned u) { return __uint_as_float(u << 16); }
; DI float bfhi(unsigned u) { return __uint_as_float(u & 0xffff0000u); }
; DI void pool_item(const Params& p, int l, int token0, char* lds) {
;     ...
;   for (int e = tid; e < 64 * 32; e += NTHREADS) {
;     const int tl = e >> 5, ch = e & 31;
;     const int g = ch >> 3;
;     const int hw = 1 << g;
;     const int s = s0 + tl;
;     int lo = s - hw; lo = lo < 0 ? 0 : lo;
;     int hi = s + hw - 1; hi = hi > L - 1 ? L - 1 : hi;
;     float sum[8];
; #pragma unroll
;     for (int j = 0; j < 8; ++j) sum[j] = 0.f;
;     for (int q = lo; q <= hi; ++q) {
;       const u32x4 v = *(const u32x4*)(zt + (q - s0 + 8) * 512 + ch * 16);
; #pragma unroll
;       for (int j = 0; j < 4; ++j) { sum[2 * j] += bflo(v[j]); sum[2 * j + 1] += bfhi(v[j]); }
;     }
;     const float ic = 1.f / (float)(hi - lo + 1);
;     const u32x4 zc = *(const u32x4*)(zt + (tl + 8) * 512 + ch * 16);
;     u32x4 ov;
; #pragma unroll
;     for (int j = 0; j < 4; ++j)
;       ov[j] = pk2(sum[2 * j] * ic - bflo(zc[j]), sum[2 * j + 1] * ic - bfhi(zc[j]));
;     *(u32x4*)(pl + tl * 512 + ((ch ^ (tl & 15)) << 4)) = ov;
;   }
	v_lshlrev_b32_e32 v228, 16, v114
	v_and_b32_e32 v229, 0xffff0000, v114
	v_pk_add_f32 v[232:233], v[232:233], v[228:229]
	v_lshlrev_b32_e32 v228, 16, v115
	v_and_b32_e32 v229, 0xffff0000, v115
	v_pk_add_f32 v[234:235], v[234:235], v[228:229]
	v_lshlrev_b32_e32 v228, 16, v116
	v_and_b32_e32 v229, 0xffff0000, v116
	v_pk_add_f32 v[236:237], v[236:237], v[228:229]
	v_lshlrev_b32_e32 v228, 16, v117
	v_and_b32_e32 v229, 0xffff0000, v117
	v_pk_add_f32 v[238:239], v[238:239], v[228:229]
	s_waitcnt lgkmcnt(4)
	v_lshlrev_b32_e32 v228, 16, v118
	v_and_b32_e32 v229, 0xffff0000, v118
	v_pk_add_f32 v[232:233], v[232:233], v[228:229]
	v_lshlrev_b32_e32 v228, 16, v119
	v_and_b32_e32 v229, 0xffff0000, v119
	v_pk_add_f32 v[234:235], v[234:235], v[228:229]
	v_lshlrev_b32_e32 v228, 16, v120
	v_and_b32_e32 v229, 0xffff0000, v120
	v_pk_add_f32 v[236:237], v[236:237], v[228:229]
	v_lshlrev_b32_e32 v228, 16, v121
	v_and_b32_e32 v229, 0xffff0000, v121
	v_pk_add_f32 v[238:239], v[238:239], v[228:229]
	s_waitcnt lgkmcnt(3)
	v_lshlrev_b32_e32 v228, 16, v122
	v_and_b32_e32 v229, 0xffff0000, v122
	v_pk_add_f32 v[232:233], v[232:233], v[228:229]
	v_lshlrev_b32_e32 v228, 16, v123
	v_and_b32_e32 v229, 0xffff0000, v123
	v_pk_add_f32 v[234:235], v[234:235], v[228:229]
	v_lshlrev_b32_e32 v228, 16, v124
	v_and_b32_e32 v229, 0xffff0000, v124
	v_pk_add_f32 v[236:237], v[236:237], v[228:229]
	v_lshlrev_b32_e32 v228, 16, v125
	v_and_b32_e32 v229, 0xffff0000, v125
	v_pk_add_f32 v[238:239], v[238:239], v[228:229]
	s_waitcnt lgkmcnt(2)
	v_lshlrev_b32_e32 v228, 16, v126
	v_and_b32_e32 v229, 0xffff0000, v126
	v_pk_add_f32 v[232:233], v[232:233], v[228:229]
	v_lshlrev_b32_e32 v228, 16, v127
	v_and_b32_e32 v229, 0xffff0000, v127
	v_pk_add_f32 v[234:235], v[234:235], v[228:229]
	v_lshlrev_b32_e32 v228, 16, v128
	v_and_b32_e32 v229, 0xffff0000, v128
	v_pk_add_f32 v[236:237], v[236:237], v[228:229]
	v_lshlrev_b32_e32 v228, 16, v129
	v_and_b32_e32 v229, 0xffff0000, v129
	v_pk_add_f32 v[238:239], v[238:239], v[228:229]
	s_waitcnt lgkmcnt(1)
	v_lshlrev_b32_e32 v228, 16, v130
	v_and_b32_e32 v229, 0xffff0000, v130
	v_pk_add_f32 v[232:233], v[232:233], v[228:229]
	v_lshlrev_b32_e32 v228, 16, v131
	v_and_b32_e32 v229, 0xffff0000, v131
	v_pk_add_f32 v[234:235], v[234:235], v[228:229]
	v_lshlrev_b32_e32 v228, 16, v132
	v_and_b32_e32 v229, 0xffff0000, v132
	v_pk_add_f32 v[236:237], v[236:237], v[228:229]
	v_lshlrev_b32_e32 v228, 16, v133
	v_and_b32_e32 v229, 0xffff0000, v133
	v_pk_add_f32 v[238:239], v[238:239], v[228:229]
	s_waitcnt lgkmcnt(0)
	v_lshlrev_b32_e32 v228, 16, v224
	v_and_b32_e32 v229, 0xffff0000, v224
	v_pk_fma_f32 v[232:233], v[158:159], v[232:233], v[228:229] op_sel_hi:[0,1,1] neg_lo:[0,0,1] neg_hi:[0,0,1]
	v_lshlrev_b32_e32 v228, 16, v225
	v_and_b32_e32 v229, 0xffff0000, v225
	v_pk_fma_f32 v[234:235], v[158:159], v[234:235], v[228:229] op_sel_hi:[0,1,1] neg_lo:[0,0,1] neg_hi:[0,0,1]
	v_lshlrev_b32_e32 v228, 16, v226
	v_and_b32_e32 v229, 0xffff0000, v226
	v_pk_fma_f32 v[236:237], v[158:159], v[236:237], v[228:229] op_sel_hi:[0,1,1] neg_lo:[0,0,1] neg_hi:[0,0,1]
	v_lshlrev_b32_e32 v228, 16, v227
	v_and_b32_e32 v229, 0xffff0000, v227
	v_pk_fma_f32 v[238:239], v[158:159], v[238:239], v[228:229] op_sel_hi:[0,1,1] neg_lo:[0,0,1] neg_hi:[0,0,1]
	v_cvt_pk_bf16_f32 v224, v232, v233
	v_cvt_pk_bf16_f32 v225, v234, v235
	v_cvt_pk_bf16_f32 v226, v236, v237
	v_cvt_pk_bf16_f32 v227, v238, v239
	v_and_b32_e32 v153, 15, v151
	v_xor_b32_e32 v153, v153, v152
	v_lshlrev_b32_e32 v154, 9, v151
	v_lshl_or_b32 v154, v153, 4, v154
	ds_write_b128 v154, v[224:227] offset:40960
	s_addk_i32 s30, 128
	s_cmpk_lt_u32 s30, 0x200
	s_cbranch_scc1 .Lpl_g2_k
	s_branch .Lpl_done
.Lpl_g3:
	s_sub_u32 s2, s28, 0
	v_mov_b32_e32 v149, s2
	v_lshl_or_b32 v149, v149, 6, v148
	s_mov_b32 s30, 0
.Lpl_g3_k:
	v_add_u32_e32 v150, s30, v149
	v_lshrrev_b32_e32 v151, 3, v150
	v_and_b32_e32 v152, 7, v150
	v_or_b32_e32 v152, 24, v152
	v_add_u32_e32 v153, 0, v151
	v_lshlrev_b32_e32 v154, 9, v153
	v_and_b32_e32 v155, 1, v153
	v_lshlrev_b32_e32 v155, 3, v155
	v_xor_b32_e32 v156, v155, v152
	v_lshl_or_b32 v156, v156, 4, v154
	v_xor_b32_e32 v155, 8, v155
	v_xor_b32_e32 v157, v155, v152
	v_lshl_or_b32 v157, v157, 4, v154
	ds_read_b128 v[102:105], v156 offset:0
	ds_read_b128 v[106:109], v157 offset:512
	ds_read_b128 v[110:113], v156 offset:1024
	ds_read_b128 v[114:117], v157 offset:1536
	ds_read_b128 v[118:121], v156 offset:2048
	ds_read_b128 v[122:125], v157 offset:2560
	ds_read_b128 v[126:129], v156 offset:3072
	ds_read_b128 v[130:133], v157 offset:3584
	ds_read_b128 v[160:163], v156 offset:4096
	ds_read_b128 v[164:167], v157 offset:4608
	ds_read_b128 v[168:171], v156 offset:5120
	ds_read_b128 v[172:175], v157 offset:5632
	ds_read_b128 v[176:179], v156 offset:6144
	ds_read_b128 v[180:183], v157 offset:6656
	ds_read_b128 v[184:187], v156 offset:7168
	ds_read_b128 v[192:195], v157 offset:7680
	v_add_u32_e32 v153, 8, v151
	v_lshlrev_b32_e32 v154, 9, v153
	v_and_b32_e32 v155, 1, v153
	v_lshlrev_b32_e32 v155, 3, v155
	v_xor_b32_e32 v155, v155, v152
	v_lshl_or_b32 v154, v155, 4, v154
	ds_read_b128 v[224:227], v154
	v_add_u32_e32 v153, s6, v151
	v_subrev_u32_e32 v154, 8, v153
	v_max_i32_e32 v154, 0, v154
	v_add_u32_e32 v155, 7, v153
	s_sub_i32 s3, s5, 1
	v_min_i32_e32 v155, s3, v155
	v_sub_u32_e32 v155, v155, v154
	v_add_u32_e32 v155, 1, v155
	v_cvt_f32_i32_e32 v155, v155
	v_div_scale_f32 v228, s[2:3], v155, v155, 1.0
	v_rcp_f32_e32 v229, v228
	s_nop 0
	v_fma_f32 v230, -v228, v229, 1.0
	v_fmac_f32_e32 v229, v230, v229
	v_div_scale_f32 v230, vcc, 1.0, v155, 1.0
	v_mul_f32_e32 v232, v230, v229
	v_fma_f32 v233, -v228, v232, v230
	v_fmac_f32_e32 v232, v233, v229
	v_fma_f32 v228, -v228, v232, v230
	v_div_fmas_f32 v228, v228, v229, v232
	v_div_fixup_f32 v158, v228, v155, 1.0
	s_waitcnt lgkmcnt(15)
; DI float bflo(unsigned u) { return __uint_as_float(u << 16); }
; DI float bfhi(unsigned u) { return __uint_as_float(u & 0xffff0000u); }
; DI void pool_item(const Params& p, int l, int token0, char* lds) {
;     ...
;     for (int q = lo; q <= hi; ++q) {
;       const u32x4 v = *(const u32x4*)(zt + (q - s0 + 8) * 512 + ch * 16);
; #pragma unroll
;       for (int j = 0; j < 4; ++j) { sum[2 * j] += bflo(v[j]); sum[2 * j + 1] += bfhi(v[j]); }
;     }
	v_lshlrev_b32_e32 v232, 16, v102
	v_and_b32_e32 v233, 0xffff0000, v102
	v_lshlrev_b32_e32 v234, 16, v103
	v_and_b32_e32 v235, 0xffff0000, v103
	v_lshlrev_b32_e32 v236, 16, v104
	v_and_b32_e32 v237, 0xffff0000, v104
	v_lshlrev_b32_e32 v238, 16, v105
	v_and_b32_e32 v239, 0xffff0000, v105
	s_waitcnt lgkmcnt(15)
	v_lshlrev_b32_e32 v228, 16, v106
	v_and_b32_e32 v229, 0xffff0000, v106
	v_pk_add_f32 v[232:233], v[232:233], v[228:229]
	v_lshlrev_b32_e32 v228, 16, v107
	v_and_b32_e32 v229, 0xffff0000, v107
	v_pk_add_f32 v[234:235], v[234:235], v[228:229]
	v_lshlrev_b32_e32 v228, 16, v108
	v_and_b32_e32 v229, 0xffff0000, v108
	v_pk_add_f32 v[236:237], v[236:237], v[228:229]
	v_lshlrev_b32_e32 v228, 16, v109
	v_and_b32_e32 v229, 0xffff0000, v109
	v_pk_add_f32 v[238:239], v[238:239], v[228:229]
	s_waitcnt lgkmcnt(14)
	v_lshlrev_b32_e32 v228, 16, v110
	v_and_b32_e32 v229, 0xffff0000, v110
	v_pk_add_f32 v[232:233], v[232:233], v[228:229]
	v_lshlrev_b32_e32 v228, 16, v111
	v_and_b32_e32 v229, 0xffff0000, v111
	v_pk_add_f32 v[234:235], v[234:235], v[228:229]
	v_lshlrev_b32_e32 v228, 16, v112
	v_and_b32_e32 v229, 0xffff0000, v112
	v_pk_add_f32 v[236:237], v[236:237], v[228:229]
	v_lshlrev_b32_e32 v228, 16, v113
	v_and_b32_e32 v229, 0xffff0000, v113
	v_pk_add_f32 v[238:239], v[238:239], v[228:229]
	s_waitcnt lgkmcnt(13)
	v_lshlrev_b32_e32 v228, 16, v114
	v_and_b32_e32 v229, 0xffff0000, v114
	v_pk_add_f32 v[232:233], v[232:233], v[228:229]
	v_lshlrev_b32_e32 v228, 16, v115
	v_and_b32_e32 v229, 0xffff0000, v115
	v_pk_add_f32 v[234:235], v[234:235], v[228:229]
	v_lshlrev_b32_e32 v228, 16, v116
	v_and_b32_e32 v229, 0xffff0000, v116
	v_pk_add_f32 v[236:237], v[236:237], v[228:229]
	v_lshlrev_b32_e32 v228, 16, v117
	v_and_b32_e32 v229, 0xffff0000, v117
	v_pk_add_f32 v[238:239], v[238:239], v[228:229]
	s_waitcnt lgkmcnt(12)
	v_lshlrev_b32_e32 v228, 16, v118
	v_and_b32_e32 v229, 0xffff0000, v118
	v_pk_add_f32 v[232:233], v[232:233], v[228:229]
	v_lshlrev_b32_e32 v228, 16, v119
	v_and_b32_e32 v229, 0xffff0000, v119
	v_pk_add_f32 v[234:235], v[234:235], v[228:229]
	v_lshlrev_b32_e32 v228, 16, v120
	v_and_b32_e32 v229, 0xffff0000, v120
	v_pk_add_f32 v[236:237], v[236:237], v[228:229]
	v_lshlrev_b32_e32 v228, 16, v121
	v_and_b32_e32 v229, 0xffff0000, v121
	v_pk_add_f32 v[238:239], v[238:239], v[228:229]
	s_waitcnt lgkmcnt(11)
	v_lshlrev_b32_e32 v228, 16, v122
	v_and_b32_e32 v229, 0xffff0000, v122
	v_pk_add_f32 v[232:233], v[232:233], v[228:229]
	v_lshlrev_b32_e32 v228, 16, v123
	v_and_b32_e32 v229, 0xffff0000, v123
	v_pk_add_f32 v[234:235], v[234:235], v[228:229]
	v_lshlrev_b32_e32 v228, 16, v124
	v_and_b32_e32 v229, 0xffff0000, v124
	v_pk_add_f32 v[236:237], v[236:237], v[228:229]
	v_lshlrev_b32_e32 v228, 16, v125
	v_and_b32_e32 v229, 0xffff0000, v125
	v_pk_add_f32 v[238:239], v[238:239], v[228:229]
	s_waitcnt lgkmcnt(10)
	v_lshlrev_b32_e32 v228, 16, v126
	v_and_b32_e32 v229, 0xffff0000, v126
	v_pk_add_f32 v[232:233], v[232:233], v[228:229]
	v_lshlrev_b32_e32 v228, 16, v127
	v_and_b32_e32 v229, 0xffff0000, v127
	v_pk_add_f32 v[234:235], v[234:235], v[228:229]
	v_lshlrev_b32_e32 v228, 16, v128
	v_and_b32_e32 v229, 0xffff0000, v128
	v_pk_add_f32 v[236:237], v[236:237], v[228:229]
	v_lshlrev_b32_e32 v228, 16, v129
	v_and_b32_e32 v229, 0xffff0000, v129
	v_pk_add_f32 v[238:239], v[238:239], v[228:229]
	s_waitcnt lgkmcnt(9)
	v_lshlrev_b32_e32 v228, 16, v130
	v_and_b32_e32 v229, 0xffff0000, v130
	v_pk_add_f32 v[232:233], v[232:233], v[228:229]
	v_lshlrev_b32_e32 v228, 16, v131
	v_and_b32_e32 v229, 0xffff0000, v131
	v_pk_add_f32 v[234:235], v[234:235], v[228:229]
	v_lshlrev_b32_e32 v228, 16, v132
	v_and_b32_e32 v229, 0xffff0000, v132
	v_pk_add_f32 v[236:237], v[236:237], v[228:229]
	v_lshlrev_b32_e32 v228, 16, v133
	v_and_b32_e32 v229, 0xffff0000, v133
	v_pk_add_f32 v[238:239], v[238:239], v[228:229]
	s_waitcnt lgkmcnt(8)
	v_lshlrev_b32_e32 v228, 16, v160
	v_and_b32_e32 v229, 0xffff0000, v160
	v_pk_add_f32 v[232:233], v[232:233], v[228:229]
	v_lshlrev_b32_e32 v228, 16, v161
	v_and_b32_e32 v229, 0xffff0000, v161
	v_pk_add_f32 v[234:235], v[234:235], v[228:229]
	v_lshlrev_b32_e32 v228, 16, v162
	v_and_b32_e32 v229, 0xffff0000, v162
	v_pk_add_f32 v[236:237], v[236:237], v[228:229]
	v_lshlrev_b32_e32 v228, 16, v163
	v_and_b32_e32 v229, 0xffff0000, v163
	v_pk_add_f32 v[238:239], v[238:239], v[228:229]
	s_waitcnt lgkmcnt(7)
	v_lshlrev_b32_e32 v228, 16, v164
	v_and_b32_e32 v229, 0xffff0000, v164
	v_pk_add_f32 v[232:233], v[232:233], v[228:229]
	v_lshlrev_b32_e32 v228, 16, v165
	v_and_b32_e32 v229, 0xffff0000, v165
	v_pk_add_f32 v[234:235], v[234:235], v[228:229]
	v_lshlrev_b32_e32 v228, 16, v166
	v_and_b32_e32 v229, 0xffff0000, v166
	v_pk_add_f32 v[236:237], v[236:237], v[228:229]
	v_lshlrev_b32_e32 v228, 16, v167
	v_and_b32_e32 v229, 0xffff0000, v167
	v_pk_add_f32 v[238:239], v[238:239], v[228:229]
	s_waitcnt lgkmcnt(6)
	v_lshlrev_b32_e32 v228, 16, v168
	v_and_b32_e32 v229, 0xffff0000, v168
	v_pk_add_f32 v[232:233], v[232:233], v[228:229]
	v_lshlrev_b32_e32 v228, 16, v169
	v_and_b32_e32 v229, 0xffff0000, v169
	v_pk_add_f32 v[234:235], v[234:235], v[228:229]
	v_lshlrev_b32_e32 v228, 16, v170
	v_and_b32_e32 v229, 0xffff0000, v170
	v_pk_add_f32 v[236:237], v[236:237], v[228:229]
	v_lshlrev_b32_e32 v228, 16, v171
	v_and_b32_e32 v229, 0xffff0000, v171
	v_pk_add_f32 v[238:239], v[238:239], v[228:229]
	s_waitcnt lgkmcnt(5)
	v_lshlrev_b32_e32 v228, 16, v172
	v_and_b32_e32 v229, 0xffff0000, v172
	v_pk_add_f32 v[232:233], v[232:233], v[228:229]
	v_lshlrev_b32_e32 v228, 16, v173
	v_and_b32_e32 v229, 0xffff0000, v173
	v_pk_add_f32 v[234:235], v[234:235], v[228:229]
	v_lshlrev_b32_e32 v228, 16, v174
	v_and_b32_e32 v229, 0xffff0000, v174
	v_pk_add_f32 v[236:237], v[236:237], v[228:229]
	v_lshlrev_b32_e32 v228, 16, v175
	v_and_b32_e32 v229, 0xffff0000, v175
	v_pk_add_f32 v[238:239], v[238:239], v[228:229]
	s_waitcnt lgkmcnt(4)
; DI float bflo(unsigned u) { return __uint_as_float(u << 16); }
; DI float bfhi(unsigned u) { return __uint_as_float(u & 0xffff0000u); }
; DI f32x16 mfma32(bf16x8 a, bf16x8 b, f32x16 c) { return __builtin_amdgcn_mfma_f32_32x32x16_bf16(a, b, c, 0, 0, 0); }
; DI void pool_item(const Params& p, int l, int token0, char* lds) {
;     ...
;     const float ic = 1.f / (float)(hi - lo + 1);
;     const u32x4 zc = *(const u32x4*)(zt + (tl + 8) * 512 + ch * 16);
;     u32x4 ov;
; #pragma unroll
;     for (int j = 0; j < 4; ++j)
;       ov[j] = pk2(sum[2 * j] * ic - bflo(zc[j]), sum[2 * j + 1] * ic - bfhi(zc[j]));
;     *(u32x4*)(pl + tl * 512 + ((ch ^ (tl & 15)) << 4)) = ov;
;   }
;   __syncthreads();
;   {
;     const int g = w & 3, tn0 = w >> 2;
;     f32x16 acc[2][2];
; #pragma unroll
;     for (int a = 0; a < 2; ++a)
; #pragma unroll
;       for (int b = 0; b < 2; ++b) acc[a][b] = zero16();
;     const bf16_t* wp = p.pwT + (size_t)((l * 4 + g) * 64) * 64;
; #pragma unroll
;     for (int ks = 0; ks < 4; ++ks) {
;       bf16x8 a[2], b[2];
; #pragma unroll
;       for (int mo = 0; mo < 2; ++mo) a[mo] = *(const bf16x8*)(wp + (size_t)(mo * 32 + r) * 64 + ks * 16 + h * 8);
;       {
;         const int row = tn0 * 32 + r;
;         const int ch = g * 8 + 2 * ks + h;
;         b[0] = *(const bf16x8*)(pl + row * 512 + ((ch ^ (row & 15)) << 4));
;       }
; #pragma unroll
;       for (int mo = 0; mo < 2; ++mo) acc[mo][0] = mfma32(a[mo], b[0], acc[mo][0]);
	v_lshlrev_b32_e32 v228, 16, v176
	v_and_b32_e32 v229, 0xffff0000, v176
	v_pk_add_f32 v[232:233], v[232:233], v[228:229]
	v_lshlrev_b32_e32 v228, 16, v177
	v_and_b32_e32 v229, 0xffff0000, v177
	v_pk_add_f32 v[234:235], v[234:235], v[228:229]
	v_lshlrev_b32_e32 v228, 16, v178
	v_and_b32_e32 v229, 0xffff0000, v178
	v_pk_add_f32 v[236:237], v[236:237], v[228:229]
	v_lshlrev_b32_e32 v228, 16, v179
	v_and_b32_e32 v229, 0xffff0000, v179
	v_pk_add_f32 v[238:239], v[238:239], v[228:229]
	s_waitcnt lgkmcnt(3)
	v_lshlrev_b32_e32 v228, 16, v180
	v_and_b32_e32 v229, 0xffff0000, v180
	v_pk_add_f32 v[232:233], v[232:233], v[228:229]
	v_lshlrev_b32_e32 v228, 16, v181
	v_and_b32_e32 v229, 0xffff0000, v181
	v_pk_add_f32 v[234:235], v[234:235], v[228:229]
	v_lshlrev_b32_e32 v228, 16, v182
	v_and_b32_e32 v229, 0xffff0000, v182
	v_pk_add_f32 v[236:237], v[236:237], v[228:229]
	v_lshlrev_b32_e32 v228, 16, v183
	v_and_b32_e32 v229, 0xffff0000, v183
	v_pk_add_f32 v[238:239], v[238:239], v[228:229]
	s_waitcnt lgkmcnt(2)
	v_lshlrev_b32_e32 v228, 16, v184
	v_and_b32_e32 v229, 0xffff0000, v184
	v_pk_add_f32 v[232:233], v[232:233], v[228:229]
	v_lshlrev_b32_e32 v228, 16, v185
	v_and_b32_e32 v229, 0xffff0000, v185
	v_pk_add_f32 v[234:235], v[234:235], v[228:229]
	v_lshlrev_b32_e32 v228, 16, v186
	v_and_b32_e32 v229, 0xffff0000, v186
	v_pk_add_f32 v[236:237], v[236:237], v[228:229]
	v_lshlrev_b32_e32 v228, 16, v187
	v_and_b32_e32 v229, 0xffff0000, v187
	v_pk_add_f32 v[238:239], v[238:239], v[228:229]
	s_waitcnt lgkmcnt(1)
	v_lshlrev_b32_e32 v228, 16, v192
	v_and_b32_e32 v229, 0xffff0000, v192
	v_pk_add_f32 v[232:233], v[232:233], v[228:229]
	v_lshlrev_b32_e32 v228, 16, v193
	v_and_b32_e32 v229, 0xffff0000, v193
	v_pk_add_f32 v[234:235], v[234:235], v[228:229]
	v_lshlrev_b32_e32 v228, 16, v194
	v_and_b32_e32 v229, 0xffff0000, v194
	v_pk_add_f32 v[236:237], v[236:237], v[228:229]
	v_lshlrev_b32_e32 v228, 16, v195
	v_and_b32_e32 v229, 0xffff0000, v195
	v_pk_add_f32 v[238:239], v[238:239], v[228:229]
	s_waitcnt lgkmcnt(0)
	v_lshlrev_b32_e32 v228, 16, v224
	v_and_b32_e32 v229, 0xffff0000, v224
	v_pk_fma_f32 v[232:233], v[158:159], v[232:233], v[228:229] op_sel_hi:[0,1,1] neg_lo:[0,0,1] neg_hi:[0,0,1]
	v_lshlrev_b32_e32 v228, 16, v225
	v_and_b32_e32 v229, 0xffff0000, v225
	v_pk_fma_f32 v[234:235], v[158:159], v[234:235], v[228:229] op_sel_hi:[0,1,1] neg_lo:[0,0,1] neg_hi:[0,0,1]
	v_lshlrev_b32_e32 v228, 16, v226
	v_and_b32_e32 v229, 0xffff0000, v226
	v_pk_fma_f32 v[236:237], v[158:159], v[236:237], v[228:229] op_sel_hi:[0,1,1] neg_lo:[0,0,1] neg_hi:[0,0,1]
	v_lshlrev_b32_e32 v228, 16, v227
	v_and_b32_e32 v229, 0xffff0000, v227
	v_pk_fma_f32 v[238:239], v[158:159], v[238:239], v[228:229] op_sel_hi:[0,1,1] neg_lo:[0,0,1] neg_hi:[0,0,1]
	v_cvt_pk_bf16_f32 v224, v232, v233
	v_cvt_pk_bf16_f32 v225, v234, v235
	v_cvt_pk_bf16_f32 v226, v236, v237
	v_cvt_pk_bf16_f32 v227, v238, v239
	v_and_b32_e32 v153, 15, v151
	v_xor_b32_e32 v153, v153, v152
	v_lshlrev_b32_e32 v154, 9, v151
	v_lshl_or_b32 v154, v153, 4, v154
	ds_write_b128 v154, v[224:227] offset:40960
	s_addk_i32 s30, 256
	s_cmpk_lt_u32 s30, 0x200
	s_cbranch_scc1 .Lpl_g3_k
.Lpl_done:
	s_waitcnt lgkmcnt(0)
	s_barrier
	s_lshr_b32 s2, s28, 2
	v_mov_b32_e32 v150, s2
	v_lshl_or_b32 v150, v150, 5, v141
	v_lshlrev_b32_e32 v151, 9, v150
	v_and_b32_e32 v152, 15, v150
	v_mov_b32_e32 v102, 0
	v_mov_b32_e32 v103, 0
	v_mov_b32_e32 v104, 0
	v_mov_b32_e32 v105, 0
	v_mov_b32_e32 v106, 0
	v_mov_b32_e32 v107, 0
	v_mov_b32_e32 v108, 0
	v_mov_b32_e32 v109, 0
	v_mov_b32_e32 v110, 0
	v_mov_b32_e32 v111, 0
	v_mov_b32_e32 v112, 0
	v_mov_b32_e32 v113, 0
	v_mov_b32_e32 v114, 0
	v_mov_b32_e32 v115, 0
	v_mov_b32_e32 v116, 0
	v_mov_b32_e32 v117, 0
	v_mov_b32_e32 v118, 0
	v_mov_b32_e32 v119, 0
	v_mov_b32_e32 v120, 0
	v_mov_b32_e32 v121, 0
	v_mov_b32_e32 v122, 0
	v_mov_b32_e32 v123, 0
	v_mov_b32_e32 v124, 0
	v_mov_b32_e32 v125, 0
	v_mov_b32_e32 v126, 0
	v_mov_b32_e32 v127, 0
	v_mov_b32_e32 v128, 0
	v_mov_b32_e32 v129, 0
	v_mov_b32_e32 v130, 0
	v_mov_b32_e32 v131, 0
	v_mov_b32_e32 v132, 0
	v_mov_b32_e32 v133, 0
	v_mov_b32_e32 v153, s29
	v_lshl_add_u32 v153, v153, 3, v142
	v_add_u32_e32 v153, 0, v153
	v_xor_b32_e32 v153, v153, v152
	v_lshl_or_b32 v153, v153, 4, v151
	ds_read_b128 v[160:163], v153 offset:40960
	v_mov_b32_e32 v153, s29
	v_lshl_add_u32 v153, v153, 3, v142
	v_add_u32_e32 v153, 2, v153
	v_xor_b32_e32 v153, v153, v152
	v_lshl_or_b32 v153, v153, 4, v151
	ds_read_b128 v[164:167], v153 offset:40960
	v_mov_b32_e32 v153, s29
	v_lshl_add_u32 v153, v153, 3, v142
	v_add_u32_e32 v153, 4, v153
	v_xor_b32_e32 v153, v153, v152
	v_lshl_or_b32 v153, v153, 4, v151
	ds_read_b128 v[168:171], v153 offset:40960
	v_mov_b32_e32 v153, s29
	v_lshl_add_u32 v153, v153, 3, v142
	v_add_u32_e32 v153, 6, v153
	v_xor_b32_e32 v153, v153, v152
	v_lshl_or_b32 v153, v153, 4, v151
	ds_read_b128 v[172:175], v153 offset:40960
	s_waitcnt vmcnt(8)
	s_waitcnt lgkmcnt(3)
	v_mfma_f32_32x32x16_bf16 v[102:117], v[38:41], v[160:163], v[102:117]
	v_mfma_f32_32x32x16_bf16 v[118:133], v[42:45], v[160:163], v[118:133]
	s_waitcnt lgkmcnt(2)
	v_mfma_f32_32x32x16_bf16 v[102:117], v[46:49], v[164:167], v[102:117]
	v_mfma_f32_32x32x16_bf16 v[118:133], v[50:53], v[164:167], v[118:133]
	s_waitcnt lgkmcnt(1)
	v_mfma_f32_32x32x16_bf16 v[102:117], v[54:57], v[168:171], v[102:117]
	v_mfma_f32_32x32x16_bf16 v[118:133], v[58:61], v[168:171], v[118:133]
	s_waitcnt lgkmcnt(0)
; DI float bflo(unsigned u) { return __uint_as_float(u << 16); }
; DI float bfhi(unsigned u) { return __uint_as_float(u & 0xffff0000u); }
; DI f32x16 mfma32(bf16x8 a, bf16x8 b, f32x16 c) { return __builtin_amdgcn_mfma_f32_32x32x16_bf16(a, b, c, 0, 0, 0); }
; DI void pool_item(const Params& p, int l, int token0, char* lds) {
;     ...
;       for (int mo = 0; mo < 2; ++mo) acc[mo][0] = mfma32(a[mo], b[0], acc[mo][0]);
;     }
;     {
;       const int tn = 0;
;       const int token = token0 + tn0 * 32 + r;
; #pragma unroll
;       for (int mo = 0; mo < 2; ++mo)
; #pragma unroll
;         for (int gg = 0; gg < 4; ++gg) {
;           const int oc = mo * 32 + 8 * gg + 4 * h;
;           const f32x4 sc = scp[mo][gg];
;           const u32x2 gv = gvp[mo][gg];
;           u32x2 ov;
;           ov[0] = pk2(acc[mo][tn][4 * gg + 0] * sc[0] * bflo(gv[0]), acc[mo][tn][4 * gg + 1] * sc[1] * bfhi(gv[0]));
;           ov[1] = pk2(acc[mo][tn][4 * gg + 2] * sc[2] * bflo(gv[1]), acc[mo][tn][4 * gg + 3] * sc[3] * bfhi(gv[1]));
;           *(u32x2*)(p.Y + (size_t)token * DM + 512 + g * 64 + oc) = ov;
;         }
;     }
;   }
;   __syncthreads();
	v_mfma_f32_32x32x16_bf16 v[102:117], v[62:65], v[172:175], v[102:117]
	v_mfma_f32_32x32x16_bf16 v[118:133], v[66:69], v[172:175], v[118:133]
	v_and_b32_e32 v154, 31, v150
	v_lshlrev_b32_e32 v155, 3, v142
	v_or_b32_e32 v155, v155, v151
	v_add_u32_e32 v155, 0x12000, v155
	v_mov_b32_e32 v153, s29
	v_lshlrev_b32_e32 v153, 3, v153
	v_or_b32_e32 v153, 0, v153
	v_xor_b32_e32 v153, v153, v154
	v_lshl_or_b32 v192, v153, 4, v155
	ds_read_b64 v[208:209], v192
	v_mov_b32_e32 v153, s29
	v_lshlrev_b32_e32 v153, 3, v153
	v_or_b32_e32 v153, 1, v153
	v_xor_b32_e32 v153, v153, v154
	v_lshl_or_b32 v193, v153, 4, v155
	ds_read_b64 v[210:211], v193
	v_mov_b32_e32 v153, s29
	v_lshlrev_b32_e32 v153, 3, v153
	v_or_b32_e32 v153, 2, v153
	v_xor_b32_e32 v153, v153, v154
	v_lshl_or_b32 v194, v153, 4, v155
	ds_read_b64 v[212:213], v194
	v_mov_b32_e32 v153, s29
	v_lshlrev_b32_e32 v153, 3, v153
	v_or_b32_e32 v153, 3, v153
	v_xor_b32_e32 v153, v153, v154
	v_lshl_or_b32 v195, v153, 4, v155
	ds_read_b64 v[214:215], v195
	v_mov_b32_e32 v153, s29
	v_lshlrev_b32_e32 v153, 3, v153
	v_or_b32_e32 v153, 4, v153
	v_xor_b32_e32 v153, v153, v154
	v_lshl_or_b32 v196, v153, 4, v155
	ds_read_b64 v[216:217], v196
	v_mov_b32_e32 v153, s29
	v_lshlrev_b32_e32 v153, 3, v153
	v_or_b32_e32 v153, 5, v153
	v_xor_b32_e32 v153, v153, v154
	v_lshl_or_b32 v197, v153, 4, v155
	ds_read_b64 v[218:219], v197
	v_mov_b32_e32 v153, s29
	v_lshlrev_b32_e32 v153, 3, v153
	v_or_b32_e32 v153, 6, v153
	v_xor_b32_e32 v153, v153, v154
	v_lshl_or_b32 v198, v153, 4, v155
	ds_read_b64 v[220:221], v198
	v_mov_b32_e32 v153, s29
	v_lshlrev_b32_e32 v153, 3, v153
	v_or_b32_e32 v153, 7, v153
	v_xor_b32_e32 v153, v153, v154
	v_lshl_or_b32 v199, v153, 4, v155
	ds_read_b64 v[222:223], v199
	s_waitcnt vmcnt(0)
	s_nop 7
	s_nop 3
	s_waitcnt lgkmcnt(7)
	v_pk_mul_f32 v[102:103], v[102:103], v[70:71]
	v_pk_mul_f32 v[104:105], v[104:105], v[72:73]
	v_lshlrev_b32_e32 v226, 16, v208
	v_and_b32_e32 v227, 0xffff0000, v208
	v_pk_mul_f32 v[102:103], v[102:103], v[226:227]
	v_lshlrev_b32_e32 v226, 16, v209
	v_and_b32_e32 v227, 0xffff0000, v209
	v_pk_mul_f32 v[104:105], v[104:105], v[226:227]
	v_cvt_pk_bf16_f32 v208, v102, v103
	v_cvt_pk_bf16_f32 v209, v104, v105
	ds_write_b64 v192, v[208:209]
	s_waitcnt lgkmcnt(6)
	v_pk_mul_f32 v[106:107], v[106:107], v[74:75]
	v_pk_mul_f32 v[108:109], v[108:109], v[76:77]
	v_lshlrev_b32_e32 v226, 16, v210
	v_and_b32_e32 v227, 0xffff0000, v210
	v_pk_mul_f32 v[106:107], v[106:107], v[226:227]
	v_lshlrev_b32_e32 v226, 16, v211
	v_and_b32_e32 v227, 0xffff0000, v211
	v_pk_mul_f32 v[108:109], v[108:109], v[226:227]
	v_cvt_pk_bf16_f32 v210, v106, v107
	v_cvt_pk_bf16_f32 v211, v108, v109
	ds_write_b64 v193, v[210:211]
	s_waitcnt lgkmcnt(5)
	v_pk_mul_f32 v[110:111], v[110:111], v[78:79]
	v_pk_mul_f32 v[112:113], v[112:113], v[80:81]
	v_lshlrev_b32_e32 v226, 16, v212
	v_and_b32_e32 v227, 0xffff0000, v212
	v_pk_mul_f32 v[110:111], v[110:111], v[226:227]
	v_lshlrev_b32_e32 v226, 16, v213
	v_and_b32_e32 v227, 0xffff0000, v213
	v_pk_mul_f32 v[112:113], v[112:113], v[226:227]
	v_cvt_pk_bf16_f32 v212, v110, v111
	v_cvt_pk_bf16_f32 v213, v112, v113
	ds_write_b64 v194, v[212:213]
	s_waitcnt lgkmcnt(4)
	v_pk_mul_f32 v[114:115], v[114:115], v[82:83]
	v_pk_mul_f32 v[116:117], v[116:117], v[84:85]
	v_lshlrev_b32_e32 v226, 16, v214
	v_and_b32_e32 v227, 0xffff0000, v214
	v_pk_mul_f32 v[114:115], v[114:115], v[226:227]
	v_lshlrev_b32_e32 v226, 16, v215
	v_and_b32_e32 v227, 0xffff0000, v215
	v_pk_mul_f32 v[116:117], v[116:117], v[226:227]
	v_cvt_pk_bf16_f32 v214, v114, v115
	v_cvt_pk_bf16_f32 v215, v116, v117
	ds_write_b64 v195, v[214:215]
	s_waitcnt lgkmcnt(3)
	v_pk_mul_f32 v[118:119], v[118:119], v[86:87]
	v_pk_mul_f32 v[120:121], v[120:121], v[88:89]
	v_lshlrev_b32_e32 v226, 16, v216
	v_and_b32_e32 v227, 0xffff0000, v216
	v_pk_mul_f32 v[118:119], v[118:119], v[226:227]
	v_lshlrev_b32_e32 v226, 16, v217
	v_and_b32_e32 v227, 0xffff0000, v217
	v_pk_mul_f32 v[120:121], v[120:121], v[226:227]
	v_cvt_pk_bf16_f32 v216, v118, v119
	v_cvt_pk_bf16_f32 v217, v120, v121
	ds_write_b64 v196, v[216:217]
	s_waitcnt lgkmcnt(2)
	v_pk_mul_f32 v[122:123], v[122:123], v[90:91]
	v_pk_mul_f32 v[124:125], v[124:125], v[92:93]
	v_lshlrev_b32_e32 v226, 16, v218
	v_and_b32_e32 v227, 0xffff0000, v218
	v_pk_mul_f32 v[122:123], v[122:123], v[226:227]
	v_lshlrev_b32_e32 v226, 16, v219
	v_and_b32_e32 v227, 0xffff0000, v219
	v_pk_mul_f32 v[124:125], v[124:125], v[226:227]
	v_cvt_pk_bf16_f32 v218, v122, v123
	v_cvt_pk_bf16_f32 v219, v124, v125
	ds_write_b64 v197, v[218:219]
	s_waitcnt lgkmcnt(1)
	v_pk_mul_f32 v[126:127], v[126:127], v[94:95]
	v_pk_mul_f32 v[128:129], v[128:129], v[96:97]
	v_lshlrev_b32_e32 v226, 16, v220
	v_and_b32_e32 v227, 0xffff0000, v220
	v_pk_mul_f32 v[126:127], v[126:127], v[226:227]
	v_lshlrev_b32_e32 v226, 16, v221
	v_and_b32_e32 v227, 0xffff0000, v221
	v_pk_mul_f32 v[128:129], v[128:129], v[226:227]
	v_cvt_pk_bf16_f32 v220, v126, v127
	v_cvt_pk_bf16_f32 v221, v128, v129
	ds_write_b64 v198, v[220:221]
	s_waitcnt lgkmcnt(0)
	v_pk_mul_f32 v[130:131], v[130:131], v[98:99]
	v_pk_mul_f32 v[132:133], v[132:133], v[100:101]
	v_lshlrev_b32_e32 v226, 16, v222
	v_and_b32_e32 v227, 0xffff0000, v222
	v_pk_mul_f32 v[130:131], v[130:131], v[226:227]
	v_lshlrev_b32_e32 v226, 16, v223
	v_and_b32_e32 v227, 0xffff0000, v223
	v_pk_mul_f32 v[132:133], v[132:133], v[226:227]
	v_cvt_pk_bf16_f32 v222, v130, v131
	v_cvt_pk_bf16_f32 v223, v132, v133
	ds_write_b64 v199, v[222:223]
	s_waitcnt lgkmcnt(0)
	s_barrier
	v_lshlrev_b32_e32 v150, 9, v134
	v_lshl_or_b32 v150, v135, 4, v150
	v_add_u32_e32 v150, 0x12000, v150
	ds_read_b128 v[160:163], v150
	ds_read_b128 v[164:167], v150 offset:8192
	ds_read_b128 v[168:171], v150 offset:16384
	ds_read_b128 v[172:175], v150 offset:24576
	v_mov_b32_e32 v0, v134
	v_and_b32_e32 v151, 31, v0
	v_xor_b32_e32 v151, v151, v135
	v_lshlrev_b32_e32 v152, 11, v0
	v_lshl_or_b32 v152, v151, 4, v152
	s_waitcnt lgkmcnt(3)
	global_store_dwordx4 v152, v[160:163], s[16:17]
	v_add_u32_e32 v0, 16, v134
	v_and_b32_e32 v151, 31, v0
	v_xor_b32_e32 v151, v151, v135
	v_lshlrev_b32_e32 v152, 11, v0
	v_lshl_or_b32 v152, v151, 4, v152
	s_waitcnt lgkmcnt(2)
	global_store_dwordx4 v152, v[164:167], s[16:17]
	v_add_u32_e32 v0, 32, v134
	v_and_b32_e32 v151, 31, v0
	v_xor_b32_e32 v151, v151, v135
	v_lshlrev_b32_e32 v152, 11, v0
	v_lshl_or_b32 v152, v151, 4, v152
	s_waitcnt lgkmcnt(1)
	global_store_dwordx4 v152, v[168:171], s[16:17]
	v_add_u32_e32 v0, 48, v134
	v_and_b32_e32 v151, 31, v0
	v_xor_b32_e32 v151, v151, v135
	v_lshlrev_b32_e32 v152, 11, v0
	v_lshl_or_b32 v152, v151, 4, v152
	s_waitcnt lgkmcnt(0)
	global_store_dwordx4 v152, v[172:175], s[16:17]
	s_barrier
	s_mov_b64 s[2:3], 0
	s_branch .LBB0_82
